# G1 epilogue: rope cos/sin rows for the next 8-row step prefetched one step ahead instead of loaded and waited inside each step
# speedup vs baseline: 1.0465x; 1.0040x over previous
.LBB0_706:
	s_or_saveexec_b64 s[24:25], s[24:25]
	v_lshlrev_b32_e32 v0, 2, v196
	v_readlane_b32 s30, v255, 30
	v_lshrrev_b32_e32 v132, 3, v196
	v_and_b32_e32 v143, 28, v0
	v_and_b32_e32 v0, 7, v200
	v_add_u32_e32 v168, s30, v167
	v_mul_u32_u24_e32 v180, 0x110, v132
	v_lshlrev_b32_e32 v144, 2, v143
	v_or_b32_e32 v169, -8, v132
	v_lshlrev_b32_e32 v182, 4, v0
	v_lshlrev_b32_e32 v138, 3, v0
	v_add_u32_e32 v181, v168, v132
	s_xor_b64 exec, exec, s[24:25]
	s_cbranch_execz .LBB0_722
	v_readlane_b32 s30, v253, 1
	v_cndmask_b32_e64 v0, v217, v218, s[26:27]
	v_readlane_b32 s31, v253, 2
	s_xor_b64 s[26:27], s[26:27], -1
	v_or_b32_e32 v152, 0x80000, v136
	v_lshl_add_u64 v[146:147], s[30:31], 0, v[0:1]
	global_load_dwordx2 v[160:161], v[146:147], off
	v_or_b32_e32 v0, 0xc0000, v150
	v_or_b32_e32 v183, -8, v132
	v_lshlrev_b64 v[132:133], 1, v[134:135]
	s_and_b64 s[30:31], s[28:29], exec
	v_cndmask_b32_e64 v150, v150, v0, s[22:23]
	v_cndmask_b32_e64 v136, v136, v152, s[22:23]
	v_mad_i64_i32 v[132:133], s[22:23], v181, s84, v[132:133]
	s_cselect_b32 s22, 0x80, 64
	v_lshl_add_u64 v[134:135], v[150:151], 1, s[92:93]
	v_cvt_f32_ubyte0_e32 v150, s22
	v_rcp_iflag_f32_e32 v150, v150
	v_cndmask_b32_e64 v153, v220, v221, s[20:21]
	v_cndmask_b32_e64 v0, v153, v222, s[28:29]
	v_sub_u32_e32 v154, 0, v130
	v_mul_f32_e32 v150, 0x4f7ffffe, v150
	v_cvt_u32_f32_e32 v153, v150
	s_cselect_b32 s34, 2, 1
	s_cselect_b32 s35, 7, 6
	v_lshlrev_b32_e32 v0, 2, v0
	s_sub_i32 s23, 0, s22
	v_max_i32_e32 v152, v130, v154
	v_lshl_add_u64 v[154:155], s[12:13], 0, v[0:1]
	v_mul_lo_u32 v0, s23, v153
	v_mul_hi_u32 v0, v153, v0
	v_add_u32_e32 v0, v153, v0
	v_lshl_add_u64 v[132:133], v[130:131], 1, v[132:133]
	v_mul_hi_u32 v0, v152, v0
	v_lshl_add_u64 v[150:151], s[14:15], 0, v[132:133]
	v_mul_lo_u32 v132, v0, s22
	v_sub_u32_e32 v132, v152, v132
	v_add_u32_e32 v133, 1, v0
	v_cmp_le_u32_e32 vcc, s22, v132
	v_readlane_b32 s28, v255, 14
	v_mov_b32_e32 v145, v1
	v_cndmask_b32_e32 v0, v0, v133, vcc
	v_subrev_u32_e32 v133, s22, v132
	v_cndmask_b32_e32 v132, v132, v133, vcc
	v_add_u32_e32 v133, 1, v0
	v_cmp_le_u32_e32 vcc, s22, v132
	v_readlane_b32 s29, v255, 15
	v_add3_u32 v184, v166, v180, v182
	v_cndmask_b32_e32 v0, v0, v133, vcc
	v_xor_b32_e32 v0, v0, v131
	v_sub_u32_e32 v152, v0, v131
	v_mul_lo_u32 v0, v152, s22
	v_sub_u32_e32 v130, v130, v0
	v_ashrrev_i32_e32 v131, 31, v130
	v_lshlrev_b64 v[132:133], 1, v[130:131]
	v_lshl_add_u64 v[130:131], v[130:131], 2, v[154:155]
	v_lshl_add_u64 v[136:137], v[136:137], 1, s[28:29]
	v_lshl_add_u64 v[158:159], v[130:131], 0, v[144:145]
	v_mov_b32_e32 v139, v1
	v_lshlrev_b32_e32 v185, 5, v181
	v_lshl_add_u64 v[146:147], s[78:79], 0, v[144:145]
	v_lshl_add_u64 v[148:149], s[6:7], 0, v[144:145]
	v_ashrrev_i32_e32 v153, 31, v152
	v_lshl_add_u64 v[154:155], v[134:135], 0, v[132:133]
	v_lshl_add_u64 v[156:157], v[136:137], 0, v[132:133]
	s_mov_b64 s[22:23], 0
	s_waitcnt vmcnt(0)
	v_lshl_add_u64 v[130:131], s[90:91], 2, v[160:161]
	v_lshl_add_u64 v[160:161], v[130:131], 0, v[144:145]
	v_and_b32_e32 v0, 0x7fe0, v185
	v_lshlrev_b32_e32 v0, 2, v0
	v_lshl_add_u64 v[250:251], v[146:147], 0, v[0:1]
	global_load_dwordx4 v[242:245], v[250:251], off
	v_lshl_add_u64 v[250:251], v[148:149], 0, v[0:1]
	global_load_dwordx4 v[246:249], v[250:251], off
	global_load_dword v227, v[250:251], off
	global_load_dword v227, v[250:251], off
	s_branch .LBB0_709

.LBB0_712:
	s_waitcnt vmcnt(2) lgkmcnt(0)
	v_mov_b64_e32 v[188:189], v[242:243]
	v_mov_b64_e32 v[190:191], v[244:245]
	v_mov_b64_e32 v[192:193], v[246:247]
	v_mov_b64_e32 v[194:195], v[248:249]
	v_add_u32_e32 v0, 0x100, v185
	v_and_b32_e32 v0, 0x7fe0, v0
	v_lshlrev_b32_e32 v0, 2, v0
	v_lshl_add_u64 v[162:163], v[146:147], 0, v[0:1]
	v_lshl_add_u64 v[250:251], v[148:149], 0, v[0:1]
	global_load_dwordx4 v[242:245], v[162:163], off
	global_load_dwordx4 v[246:249], v[250:251], off
	v_pk_mul_f32 v[162:163], v[130:131], v[192:193]
	s_nop 0
	v_pk_fma_f32 v[162:163], v[134:135], v[188:189], v[162:163] neg_lo:[0,0,1] neg_hi:[0,0,1]
	v_pk_mul_f32 v[134:135], v[134:135], v[192:193]
	s_nop 0
	v_pk_fma_f32 v[130:131], v[130:131], v[188:189], v[134:135]
	v_pk_mul_f32 v[134:135], v[132:133], v[194:195]
	s_nop 0
	v_pk_fma_f32 v[134:135], v[136:137], v[190:191], v[134:135] neg_lo:[0,0,1] neg_hi:[0,0,1]
	v_pk_mul_f32 v[136:137], v[136:137], v[194:195]
	s_nop 0
	v_pk_fma_f32 v[132:133], v[132:133], v[190:191], v[136:137]
	v_mov_b64_e32 v[136:137], v[134:135]
	v_mov_b64_e32 v[134:135], v[162:163]

.LBB0_765:
	s_andn2_saveexec_b64 s[22:23], s[22:23]
	s_cbranch_execz .LBB0_781
	v_readlane_b32 s26, v253, 1
	v_cndmask_b32_e64 v0, v217, v218, s[24:25]
	v_readlane_b32 s27, v253, 2
	v_cndmask_b32_e64 v153, 64, v219, s[30:31]
	v_cndmask_b32_e64 v154, v220, v221, s[20:21]
	v_lshl_add_u64 v[132:133], s[26:27], 0, v[0:1]
	global_load_dwordx2 v[132:133], v[132:133], off
	v_or_b32_e32 v0, 0xc0000, v136
	v_cndmask_b32_e64 v136, v136, v0, s[28:29]
	v_cndmask_b32_e64 v0, v154, v222, s[30:31]
	v_cvt_f32_ubyte0_e32 v154, v153
	v_lshlrev_b64 v[134:135], 1, v[134:135]
	v_rcp_iflag_f32_e32 v154, v154
	v_mad_i64_i32 v[134:135], s[26:27], v181, s84, v[134:135]
	v_or_b32_e32 v152, 0x80000, v150
	v_readlane_b32 s26, v255, 14
	v_cndmask_b32_e64 v150, v150, v152, s[28:29]
	v_readlane_b32 s27, v255, 15
	v_sub_u32_e32 v155, 0, v130
	v_sub_u32_e32 v158, 0, v153
	v_lshl_add_u64 v[156:157], v[150:151], 1, s[26:27]
	v_mul_f32_e32 v150, 0x4f7ffffe, v154
	v_cvt_u32_f32_e32 v159, v150
	v_lshlrev_b32_e32 v0, 2, v0
	v_max_i32_e32 v152, v130, v155
	v_lshl_add_u64 v[154:155], s[12:13], 0, v[0:1]
	v_mul_lo_u32 v0, v158, v159
	v_mul_hi_u32 v0, v159, v0
	v_add_u32_e32 v0, v159, v0
	v_lshl_add_u64 v[134:135], v[130:131], 1, v[134:135]
	v_mul_hi_u32 v0, v152, v0
	v_lshl_add_u64 v[150:151], s[14:15], 0, v[134:135]
	v_mul_lo_u32 v134, v0, v153
	v_sub_u32_e32 v134, v152, v134
	v_add_u32_e32 v135, 1, v0
	v_cmp_ge_u32_e32 vcc, v134, v153
	v_mov_b32_e32 v145, v1
	v_lshl_add_u64 v[136:137], v[136:137], 1, s[92:93]
	v_cndmask_b32_e32 v0, v0, v135, vcc
	v_sub_u32_e32 v135, v134, v153
	v_cndmask_b32_e32 v134, v134, v135, vcc
	v_add_u32_e32 v135, 1, v0
	v_cmp_ge_u32_e32 vcc, v134, v153
	s_xor_b64 s[24:25], s[24:25], -1
	v_cndmask_b32_e64 v140, 1, 2, s[30:31]
	v_cndmask_b32_e32 v0, v0, v135, vcc
	v_xor_b32_e32 v0, v0, v131
	v_sub_u32_e32 v152, v0, v131
	v_mul_lo_u32 v0, v152, v153
	v_sub_u32_e32 v130, v130, v0
	v_ashrrev_i32_e32 v131, 31, v130
	v_lshlrev_b64 v[134:135], 1, v[130:131]
	v_lshl_add_u64 v[130:131], v[130:131], 2, v[154:155]
	v_lshl_add_u64 v[158:159], v[130:131], 0, v[144:145]
	v_cndmask_b32_e64 v142, 6, 7, s[30:31]
	v_add3_u32 v141, v166, v180, v182
	v_mov_b32_e32 v139, v1
	v_lshlrev_b32_e32 v162, 5, v181
	v_lshl_add_u64 v[146:147], s[78:79], 0, v[144:145]
	v_lshl_add_u64 v[148:149], s[6:7], 0, v[144:145]
	v_ashrrev_i32_e32 v153, 31, v152
	v_lshl_add_u64 v[154:155], v[136:137], 0, v[134:135]
	v_lshl_add_u64 v[156:157], v[156:157], 0, v[134:135]
	s_mov_b64 s[26:27], 0
	s_waitcnt vmcnt(0)
	v_lshl_add_u64 v[130:131], s[90:91], 2, v[132:133]
	v_lshl_add_u64 v[144:145], v[130:131], 0, v[144:145]
	v_and_b32_e32 v0, 0x7fe0, v162
	v_lshlrev_b32_e32 v0, 2, v0
	v_lshl_add_u64 v[250:251], v[146:147], 0, v[0:1]
	global_load_dwordx4 v[242:245], v[250:251], off
	v_lshl_add_u64 v[250:251], v[148:149], 0, v[0:1]
	global_load_dwordx4 v[246:249], v[250:251], off
	global_load_dword v227, v[250:251], off
	global_load_dword v227, v[250:251], off
	s_branch .LBB0_768

.LBB0_771:
	s_waitcnt vmcnt(2) lgkmcnt(0)
	v_mov_b64_e32 v[170:171], v[242:243]
	v_mov_b64_e32 v[172:173], v[244:245]
	v_mov_b64_e32 v[174:175], v[246:247]
	v_mov_b64_e32 v[176:177], v[248:249]
	v_add_u32_e32 v0, 0x100, v162
	v_and_b32_e32 v0, 0x7fe0, v0
	v_lshlrev_b32_e32 v0, 2, v0
	v_lshl_add_u64 v[160:161], v[146:147], 0, v[0:1]
	v_lshl_add_u64 v[250:251], v[148:149], 0, v[0:1]
	global_load_dwordx4 v[242:245], v[160:161], off
	global_load_dwordx4 v[246:249], v[250:251], off
	v_pk_mul_f32 v[160:161], v[130:131], v[174:175]
	s_nop 0
	v_pk_fma_f32 v[160:161], v[134:135], v[170:171], v[160:161] neg_lo:[0,0,1] neg_hi:[0,0,1]
	v_pk_mul_f32 v[134:135], v[134:135], v[174:175]
	s_nop 0
	v_pk_fma_f32 v[130:131], v[130:131], v[170:171], v[134:135]
	v_pk_mul_f32 v[134:135], v[132:133], v[176:177]
	s_nop 0
	v_pk_fma_f32 v[134:135], v[136:137], v[172:173], v[134:135] neg_lo:[0,0,1] neg_hi:[0,0,1]
	v_pk_mul_f32 v[136:137], v[136:137], v[176:177]
	s_nop 0
	v_pk_fma_f32 v[132:133], v[132:133], v[172:173], v[136:137]
	v_mov_b64_e32 v[136:137], v[134:135]
	v_mov_b64_e32 v[134:135], v[160:161]
